# norm_rows loops (P6, P9 non-final): gain vector loaded once before the row loop, per-row reload batches and their vmcnt(0) drains removed; on top of scan rewrite
# speedup vs baseline: 1.0120x; 1.0005x over previous
; __device__ __forceinline__ const float* karg(int k) { int kk = k; asm volatile("" : "+s"(kk)); return ((const float* const __attribute__((address_space(4)))*)__builtin_amdgcn_kernarg_segment_ptr())[kk]; }
; template <bool FINAL, bool DUMMY = false> __device__ __forceinline__ void norm_rows(const bfu* F, bfu* XB, const float* g1, float* RS, float* xout, int gw, int NGW, int lane, bfu* dummy = nullptr) {
;     int m = gw; if (m >= M) return;
;     v4u fw[4], xw[4];
; #pragma unroll
;     for (int j = 0; j < 4; ++j) { fw[j] = __builtin_nontemporal_load((const v4u*)(F + (size_t)m * DM) + lane + 64 * j); xw[j] = ((const v4u*)(XB + (size_t)m * DM) + lane)[64 * j]; }
;     for (; m < M; m += NGW) {
;         f32x4 f[8], x[8]; float s = 0.f;
; #pragma unroll
;         for (int j = 0; j < 4; ++j) {
;             f[2 * j] = (f32x4){bflo(fw[j].x), bfhi(fw[j].x), bflo(fw[j].y), bfhi(fw[j].y)}; f[2 * j + 1] = (f32x4){bflo(fw[j].z), bfhi(fw[j].z), bflo(fw[j].w), bfhi(fw[j].w)};
;             x[2 * j] = (f32x4){bflo(xw[j].x), bfhi(xw[j].x), bflo(xw[j].y), bfhi(xw[j].y)}; x[2 * j + 1] = (f32x4){bflo(xw[j].z), bfhi(xw[j].z), bflo(xw[j].w), bfhi(xw[j].w)}; }
;         const int mn = m + NGW;
;         if (mn < M) {
; #pragma unroll
;             for (int j = 0; j < 4; ++j) { fw[j] = __builtin_nontemporal_load((const v4u*)(F + (size_t)mn * DM) + lane + 64 * j); xw[j] = ((const v4u*)(XB + (size_t)mn * DM) + lane)[64 * j]; }
;         }
; #pragma unroll
;         for (int k = 0; k < 8; ++k) s += (f[k].x * f[k].x + f[k].y * f[k].y) + (f[k].z * f[k].z + f[k].w * f[k].w);
;         const float rstd1 = 1.f / sqrtf(wave_sum(s) * (1.f / DM) + EPS);
;         float s2 = 0.f;
; #pragma unroll
;         for (int k = 0; k < 8; ++k) { const f32x4 gg = ((const f32x4*)g1)[2 * lane + 128 * (k >> 1) + (k & 1)]; x[k] = x[k] + f[k] * rstd1 * gg; s2 += (x[k].x * x[k].x + x[k].y * x[k].y) + (x[k].z * x[k].z + x[k].w * x[k].w); }
; __global__ void __launch_bounds__(NTHR, 2) fwd(Args args) {
;     ...
;         if (XEN(6) && IN_PH()) for (int rep = 0; rep < XREP(6); ++rep) { PIN_TID(); if (XREP(6) > 1 && rep == 0) norm_rows<false, true>(F32, XN, karg(14) + l * DM, RS, nullptr, gw, NGW, lane, PROJ); else norm_rows<false>(F32, XN, karg(14) + l * DM, RS, nullptr, gw, NGW, lane); }
.LBB0_632:
	s_cmp_le_i32 s58, s20
	s_cselect_b64 s[4:5], -1, 0
	s_and_b64 s[22:23], s[4:5], s[26:27]
	s_andn2_b64 vcc, exec, s[22:23]
	s_cbranch_vccnz .LBB0_640
	v_mov_b32_e32 v0, v232
	s_mov_b32 s42, 21
	v_readfirstlane_b32 s20, v0
	s_ashr_i32 s22, s20, 6
	v_readlane_b32 s20, v255, 25
	s_add_i32 s26, s22, s20
	s_mov_b32 s40, 21
	s_mov_b32 s36, 14
	s_mov_b32 s34, 21
	s_cmpk_gt_i32 s26, 0x3fff
	s_cbranch_scc1 .LBB0_640
	s_ashr_i32 s43, s42, 31
	s_lshl_b64 s[42:43], s[42:43], 3
	s_add_u32 s42, s0, s42
	s_addc_u32 s43, s1, s43
	s_ashr_i32 s41, s40, 31
	s_lshl_b64 s[40:41], s[40:41], 3
	s_add_u32 s40, s0, s40
	s_addc_u32 s41, s1, s41
	s_ashr_i32 s37, s36, 31
	s_lshl_b64 s[36:37], s[36:37], 3
	s_add_u32 s36, s0, s36
	s_addc_u32 s37, s1, s37
	s_ashr_i32 s35, s34, 31
	s_lshl_b64 s[34:35], s[34:35], 3
	s_add_u32 s44, s0, s34
	s_addc_u32 s45, s1, s35
	s_load_dwordx2 s[34:35], s[42:43], 0x0
	s_nop 0
	s_load_dwordx2 s[36:37], s[36:37], 0x0
	s_nop 0
	s_load_dwordx2 s[44:45], s[44:45], 0x0
	s_nop 0
	s_load_dwordx2 s[42:43], s[40:41], 0x0
	v_readlane_b32 s20, v255, 30
	s_lshl_b32 s20, s20, 11
	s_lshl_b64 s[40:41], s[20:21], 2
	s_waitcnt lgkmcnt(0)
	s_add_u32 s46, s36, s40
	s_addc_u32 s47, s37, s41
	s_ashr_i32 s27, s26, 31
	s_lshl_b64 s[40:41], s[26:27], 12
	v_and_b32_e32 v10, 63, v0
	s_add_u32 s36, s42, s40
	v_lshlrev_b32_e32 v0, 4, v10
	s_addc_u32 s37, s43, s41
	v_lshl_add_u64 v[2:3], s[36:37], 0, v[0:1]
	s_mov_b64 s[48:49], 0x18e00000
	s_add_u32 s40, s34, s40
	s_mov_b32 s20, 0x18e00000
	v_lshl_add_u64 v[4:5], v[2:3], 0, s[48:49]
	s_addc_u32 s41, s35, s41
	v_add_co_u32_e32 v2, vcc, s20, v2
	v_lshl_add_u64 v[6:7], s[40:41], 0, v[0:1]
	s_nop 0
	v_addc_co_u32_e32 v3, vcc, 0, v3, vcc
	s_mov_b32 s20, 0x2d600000
	global_load_dwordx4 v[34:37], v[4:5], off offset:3072
	global_load_dwordx4 v[42:45], v[4:5], off offset:2048
	global_load_dwordx4 v[50:53], v[4:5], off offset:1024
	global_load_dwordx4 v[54:57], v[2:3], off
	v_add_co_u32_e32 v2, vcc, s20, v6
	s_mov_b64 s[40:41], 0x2d600000
	s_nop 0
	v_addc_co_u32_e32 v3, vcc, 0, v7, vcc
	v_lshl_add_u64 v[8:9], v[6:7], 0, s[40:41]
	global_load_dwordx4 v[62:65], v[2:3], off nt
	global_load_dwordx4 v[58:61], v[8:9], off offset:1024 nt
	global_load_dwordx4 v[46:49], v[8:9], off offset:2048 nt
	global_load_dwordx4 v[38:41], v[8:9], off offset:3072 nt
	v_and_b32_e32 v2, 64, v240
	v_mov_b32_e32 v3, v1
	v_add_u32_e32 v11, 64, v2
	v_lshlrev_b32_e32 v2, 5, v10
	v_lshl_add_u64 v[66:67], s[46:47], 0, v[2:3]
	s_mov_b64 s[46:47], 0x1000
	v_lshl_add_u64 v[68:69], v[66:67], 0, s[46:47]
	s_mov_b64 s[46:47], 0x1800
	v_lshl_add_u64 v[70:71], v[66:67], 0, s[46:47]
	global_load_dwordx4 v[128:131], v[66:67], off offset:16
	global_load_dwordx4 v[132:135], v[66:67], off
	global_load_dwordx4 v[136:139], v[66:67], off offset:2064
	global_load_dwordx4 v[140:143], v[66:67], off offset:2048
	global_load_dwordx4 v[144:147], v[68:69], off offset:16
	global_load_dwordx4 v[148:151], v[68:69], off
	global_load_dwordx4 v[152:155], v[70:71], off offset:16
	global_load_dwordx4 v[156:159], v[70:71], off
	s_waitcnt vmcnt(0)
	s_lshl_b64 s[46:47], s[26:27], 2
	v_xor_b32_e32 v4, 1, v240
	s_add_u32 s20, s44, s46
	v_xor_b32_e32 v5, 2, v240
	v_cmp_lt_i32_e32 vcc, v4, v11
	s_addc_u32 s23, s45, s47
	v_xor_b32_e32 v6, 4, v240
	v_cndmask_b32_e32 v4, v240, v4, vcc
	v_cmp_lt_i32_e32 vcc, v5, v11
	s_add_u32 s44, s20, 0x1c0000
	v_readlane_b32 s20, v255, 26
	v_xor_b32_e32 v7, 8, v240
	v_cndmask_b32_e32 v5, v240, v5, vcc
	v_cmp_lt_i32_e32 vcc, v6, v11
	s_addc_u32 s45, s23, 0
	s_add_i32 s22, s20, s22
	v_xor_b32_e32 v8, 16, v240
	v_cndmask_b32_e32 v6, v240, v6, vcc
	v_cmp_lt_i32_e32 vcc, v7, v11
	s_ashr_i32 s23, s22, 31
	v_xor_b32_e32 v9, 32, v240
	v_cndmask_b32_e32 v7, v240, v7, vcc
	v_cmp_lt_i32_e32 vcc, v8, v11
	s_lshl_b64 s[22:23], s[22:23], 12
	s_add_u32 s46, s34, s22
	v_cndmask_b32_e32 v8, v240, v8, vcc
	v_cmp_lt_i32_e32 vcc, v9, v11
	s_addc_u32 s47, s35, s23
	v_cmp_eq_u32_e64 s[40:41], 0, v10
	v_cndmask_b32_e32 v9, v240, v9, vcc
	v_lshlrev_b32_e32 v116, 2, v4
	v_lshlrev_b32_e32 v117, 2, v5
	v_lshlrev_b32_e32 v118, 2, v6
	v_lshlrev_b32_e32 v119, 2, v7
	v_lshlrev_b32_e32 v120, 2, v8
	v_lshlrev_b32_e32 v121, 2, v9
	s_add_u32 s50, s42, s22
	s_addc_u32 s51, s43, s23
	s_waitcnt vmcnt(0)
	v_mov_b64_e32 v[18:19], v[42:43]
	v_mov_b64_e32 v[10:11], v[50:51]
	v_mov_b64_e32 v[2:3], v[54:55]
	v_mov_b64_e32 v[22:23], v[34:35]
	v_mov_b64_e32 v[4:5], v[56:57]
	v_mov_b64_e32 v[12:13], v[52:53]
	v_mov_b64_e32 v[6:7], v[62:63]
	v_mov_b64_e32 v[14:15], v[58:59]
	v_mov_b64_e32 v[26:27], v[46:47]
	v_mov_b64_e32 v[30:31], v[38:39]
	v_mov_b64_e32 v[20:21], v[44:45]
	v_mov_b64_e32 v[24:25], v[36:37]
	v_mov_b64_e32 v[8:9], v[64:65]
	v_mov_b64_e32 v[16:17], v[60:61]
	v_mov_b64_e32 v[28:29], v[48:49]
	v_mov_b64_e32 v[32:33], v[40:41]
	s_branch .LBB0_636

; template <bool FINAL, bool DUMMY = false> __device__ __forceinline__ void norm_rows(const bfu* F, bfu* XB, const float* g1, float* RS, float* xout, int gw, int NGW, int lane, bfu* dummy = nullptr) {
;     ...
;     for (; m < M; m += NGW) {
;         f32x4 f[8], x[8]; float s = 0.f;
; #pragma unroll
;         for (int j = 0; j < 4; ++j) {
;             f[2 * j] = (f32x4){bflo(fw[j].x), bfhi(fw[j].x), bflo(fw[j].y), bfhi(fw[j].y)}; f[2 * j + 1] = (f32x4){bflo(fw[j].z), bfhi(fw[j].z), bflo(fw[j].w), bfhi(fw[j].w)};
;             x[2 * j] = (f32x4){bflo(xw[j].x), bfhi(xw[j].x), bflo(xw[j].y), bfhi(xw[j].y)}; x[2 * j + 1] = (f32x4){bflo(xw[j].z), bfhi(xw[j].z), bflo(xw[j].w), bfhi(xw[j].w)}; }
;         const int mn = m + NGW;
;         if (mn < M) {
; #pragma unroll
;             for (int j = 0; j < 4; ++j) { fw[j] = __builtin_nontemporal_load((const v4u*)(F + (size_t)mn * DM) + lane + 64 * j); xw[j] = ((const v4u*)(XB + (size_t)mn * DM) + lane)[64 * j]; }
;         }
; #pragma unroll
;         for (int k = 0; k < 8; ++k) s += (f[k].x * f[k].x + f[k].y * f[k].y) + (f[k].z * f[k].z + f[k].w * f[k].w);
;         const float rstd1 = 1.f / sqrtf(wave_sum(s) * (1.f / DM) + EPS);
.LBB0_638:
	v_lshlrev_b32_e32 v73, 16, v64
	v_and_b32_e32 v107, 0xffff0000, v64
	v_and_b32_e32 v106, 0xffff0000, v62
	v_lshlrev_b32_e32 v109, 16, v65
	v_and_b32_e32 v65, 0xffff0000, v65
	v_and_b32_e32 v64, 0xffff0000, v63
	v_lshlrev_b32_e32 v72, 16, v62
	v_lshlrev_b32_e32 v108, 16, v63
	v_lshlrev_b32_e32 v110, 16, v56
	v_and_b32_e32 v111, 0xffff0000, v56
	v_lshlrev_b32_e32 v112, 16, v57
	v_and_b32_e32 v113, 0xffff0000, v57
	v_lshlrev_b32_e32 v98, 16, v52
	v_and_b32_e32 v99, 0xffff0000, v52
	v_lshlrev_b32_e32 v100, 16, v53
	v_and_b32_e32 v101, 0xffff0000, v53
	v_lshlrev_b32_e32 v75, 16, v49
	v_lshlrev_b32_e32 v74, 16, v48
	v_and_b32_e32 v77, 0xffff0000, v49
	v_and_b32_e32 v76, 0xffff0000, v48
	v_lshlrev_b32_e32 v86, 16, v42
	v_and_b32_e32 v87, 0xffff0000, v42
	v_lshlrev_b32_e32 v88, 16, v43
	v_and_b32_e32 v89, 0xffff0000, v43
	v_lshlrev_b32_e32 v52, 16, v34
	v_and_b32_e32 v53, 0xffff0000, v34
	v_lshlrev_b32_e32 v56, 16, v35
	v_and_b32_e32 v57, 0xffff0000, v35
	v_lshlrev_b32_e32 v42, 16, v36
	v_and_b32_e32 v43, 0xffff0000, v36
	v_lshlrev_b32_e32 v48, 16, v37
	v_and_b32_e32 v49, 0xffff0000, v37
	v_pk_mul_f32 v[34:35], v[106:107], v[106:107]
	v_pk_mul_f32 v[36:37], v[64:65], v[64:65]
	v_pk_fma_f32 v[34:35], v[72:73], v[72:73], v[34:35]
	v_pk_fma_f32 v[36:37], v[108:109], v[108:109], v[36:37]
	v_and_b32_e32 v93, 0xffff0000, v59
	v_and_b32_e32 v92, 0xffff0000, v58
	v_pk_add_f32 v[34:35], v[34:35], v[36:37]
	v_lshlrev_b32_e32 v91, 16, v59
	v_lshlrev_b32_e32 v90, 16, v58
	v_lshlrev_b32_e32 v94, 16, v60
	v_and_b32_e32 v95, 0xffff0000, v60
	v_lshlrev_b32_e32 v96, 16, v61
	v_lshlrev_b32_e32 v82, 16, v46
	v_pk_add_f32 v[34:35], v[34:35], v[34:35] op_sel_hi:[0,1]
	v_pk_mul_f32 v[36:37], v[92:93], v[92:93]
	v_lshlrev_b32_e32 v114, 16, v54
	v_and_b32_e32 v115, 0xffff0000, v54
	v_lshlrev_b32_e32 v62, 16, v55
	v_and_b32_e32 v63, 0xffff0000, v55
	v_and_b32_e32 v97, 0xffff0000, v61
	v_lshlrev_b32_e32 v102, 16, v50
	v_and_b32_e32 v103, 0xffff0000, v50
	v_lshlrev_b32_e32 v104, 16, v51
	v_and_b32_e32 v105, 0xffff0000, v51
	v_lshlrev_b32_e32 v50, 16, v38
	v_and_b32_e32 v51, 0xffff0000, v38
	v_lshlrev_b32_e32 v54, 16, v39
	v_and_b32_e32 v55, 0xffff0000, v39
	v_pk_fma_f32 v[36:37], v[90:91], v[90:91], v[36:37]
	v_mul_f32_e32 v83, v94, v94
	v_mul_f32_e32 v39, v95, v95
	v_mul_f32_e32 v34, v96, v96
	v_mov_b32_e32 v38, v82
	v_and_b32_e32 v122, 0xffff0000, v46
	v_lshlrev_b32_e32 v84, 16, v47
	v_and_b32_e32 v85, 0xffff0000, v47
	v_lshlrev_b32_e32 v78, 16, v44
	v_and_b32_e32 v79, 0xffff0000, v44
	v_lshlrev_b32_e32 v80, 16, v45
	v_and_b32_e32 v81, 0xffff0000, v45
	v_lshlrev_b32_e32 v46, 16, v40
	v_and_b32_e32 v59, 0xffff0000, v40
	v_lshlrev_b32_e32 v44, 16, v41
	v_and_b32_e32 v45, 0xffff0000, v41
	v_pk_add_f32 v[36:37], v[36:37], v[36:37] op_sel_hi:[0,1]
	v_pk_fma_f32 v[40:41], v[96:97], v[96:97], v[34:35] op_sel_hi:[1,1,0]
	v_pk_add_f32 v[38:39], v[82:83], v[38:39]
	v_mul_f32_e32 v40, v122, v122
	v_mul_f32_e32 v34, v84, v84
	v_mul_f32_e32 v36, v85, v85
	v_mul_f32_e32 v60, v82, v82
	v_mov_b32_e32 v61, v39
	v_pk_add_f32 v[38:39], v[60:61], v[40:41]
	v_pk_add_f32 v[34:35], v[34:35], v[36:37]
	v_pk_mul_f32 v[36:37], v[76:77], v[76:77]
	v_pk_add_f32 v[34:35], v[38:39], v[34:35]
	v_pk_fma_f32 v[36:37], v[74:75], v[74:75], v[36:37]
	v_pk_add_f32 v[34:35], v[34:35], v[34:35] op_sel_hi:[0,1]
	v_mul_f32_e32 v47, v50, v50
	v_mul_f32_e32 v39, v51, v51
	v_mul_f32_e32 v34, v54, v54
	v_mov_b32_e32 v38, v46
	v_pk_add_f32 v[36:37], v[36:37], v[36:37] op_sel_hi:[0,1]
	v_pk_fma_f32 v[40:41], v[54:55], v[54:55], v[34:35] op_sel_hi:[1,1,0]
	v_pk_add_f32 v[38:39], v[46:47], v[38:39]
	v_mul_f32_e32 v40, v59, v59
	v_mul_f32_e32 v36, v44, v44
	v_mul_f32_e32 v34, v45, v45
	v_mul_f32_e32 v60, v46, v46
	v_mov_b32_e32 v61, v39
	v_pk_add_f32 v[38:39], v[60:61], v[40:41]
	v_pk_add_f32 v[34:35], v[36:37], v[34:35]
	v_mov_b32_e32 v60, v72
	v_pk_add_f32 v[34:35], v[38:39], v[34:35]
	v_mov_b32_e32 v61, v106
	v_add_f32_e32 v34, v34, v35
	ds_bpermute_b32 v35, v116, v34
	v_mov_b32_e32 v124, v108
	v_mov_b32_e32 v125, v64
	v_mov_b32_e32 v106, v73
	v_mov_b32_e32 v64, v109
	s_waitcnt lgkmcnt(0)
	v_add_f32_e32 v34, v34, v35
	ds_bpermute_b32 v35, v117, v34
	v_mov_b32_e32 v83, v122
	s_mov_b32 s20, 0x18e00000
	s_waitcnt lgkmcnt(0)
	v_add_f32_e32 v34, v34, v35
	ds_bpermute_b32 v35, v118, v34
	s_waitcnt lgkmcnt(0)
	v_add_f32_e32 v34, v34, v35
	ds_bpermute_b32 v35, v119, v34
	s_waitcnt lgkmcnt(0)
	v_add_f32_e32 v34, v34, v35
	ds_bpermute_b32 v35, v120, v34
	s_waitcnt lgkmcnt(0)
	v_add_f32_e32 v34, v34, v35
	ds_bpermute_b32 v35, v121, v34
	s_waitcnt lgkmcnt(0)
; __device__ __forceinline__ unsigned pk2(float lo, float hi) { return pg8::cvt_pk_bf16(lo, hi); }
; template <bool FINAL, bool DUMMY = false> __device__ __forceinline__ void norm_rows(const bfu* F, bfu* XB, const float* g1, float* RS, float* xout, int gw, int NGW, int lane, bfu* dummy = nullptr) {
;     ...
;         const float rstd1 = 1.f / sqrtf(wave_sum(s) * (1.f / DM) + EPS);
;         float s2 = 0.f;
; #pragma unroll
;         for (int k = 0; k < 8; ++k) { const f32x4 gg = ((const f32x4*)g1)[2 * lane + 128 * (k >> 1) + (k & 1)]; x[k] = x[k] + f[k] * rstd1 * gg; s2 += (x[k].x * x[k].x + x[k].y * x[k].y) + (x[k].z * x[k].z + x[k].w * x[k].w); }
;         if (FINAL) { f32x4* xo = (f32x4*)(xout + (size_t)m * DM);
; #pragma unroll
;             for (int k = 0; k < 8; ++k) __builtin_nontemporal_store(x[k], xo + 2 * lane + 128 * (k >> 1) + (k & 1));
;         } else {
;             v4u* xr = (v4u*)((DUMMY ? dummy : XB) + (size_t)m * DM) + lane;
; #pragma unroll
;             for (int j = 0; j < 4; ++j) { v4u w; w.x = pk2(x[2 * j].x, x[2 * j].y); w.y = pk2(x[2 * j].z, x[2 * j].w); w.z = pk2(x[2 * j + 1].x, x[2 * j + 1].y); w.w = pk2(x[2 * j + 1].z, x[2 * j + 1].w); xr[64 * j] = w; }
;             const float rstd2 = 1.f / sqrtf(wave_sum(s2) * (1.f / DM) + EPS);
;             if (lane == 0) (DUMMY ? (float*)dummy + (size_t)M * DM : RS)[m] = rstd2;
	v_add_f32_e32 v34, v34, v35
	v_fmamk_f32 v34, v34, 0x3a000000, v236
	v_cmp_gt_f32_e32 vcc, s68, v34
	v_mul_f32_e32 v35, 0x4f800000, v34
	s_nop 0
	v_cndmask_b32_e32 v34, v34, v35, vcc
	v_sqrt_f32_e32 v35, v34
	s_nop 0
	v_add_u32_e32 v36, -1, v35
	v_fma_f32 v37, -v36, v35, v34
	v_cmp_ge_f32_e64 s[42:43], 0, v37
	v_add_u32_e32 v37, 1, v35
	s_nop 0
	v_cndmask_b32_e64 v36, v35, v36, s[42:43]
	v_fma_f32 v35, -v37, v35, v34
	v_cmp_lt_f32_e64 s[42:43], 0, v35
	s_nop 1
	v_cndmask_b32_e64 v35, v36, v37, s[42:43]
	v_mul_f32_e32 v36, 0x37800000, v35
	v_cndmask_b32_e32 v35, v35, v36, vcc
	v_cmp_class_f32_e32 vcc, v34, v234
	s_nop 1
	v_cndmask_b32_e32 v34, v35, v34, vcc
	v_div_scale_f32 v35, s[22:23], v34, v34, 1.0
	v_rcp_f32_e32 v36, v35
	s_nop 0
	v_fma_f32 v37, -v35, v36, 1.0
	v_fmac_f32_e32 v36, v37, v36
	v_div_scale_f32 v37, vcc, 1.0, v34, 1.0
	v_mul_f32_e32 v38, v37, v36
	v_fma_f32 v39, -v35, v38, v37
	v_fmac_f32_e32 v38, v39, v36
	v_fma_f32 v35, -v35, v38, v37
	v_div_fmas_f32 v35, v35, v36, v38
	v_div_fixup_f32 v58, v35, v34, 1.0
	v_pk_mul_f32 v[60:61], v[58:59], v[60:61] op_sel_hi:[0,1]
	v_pk_mul_f32 v[124:125], v[58:59], v[124:125] op_sel_hi:[0,1]
	v_pk_mul_f32 v[50:51], v[58:59], v[50:51] op_sel_hi:[0,1]
	v_pk_mul_f32 v[54:55], v[58:59], v[54:55] op_sel_hi:[0,1]
	v_pk_mul_f32 v[44:45], v[58:59], v[44:45] op_sel_hi:[0,1]
	v_pk_fma_f32 v[62:63], v[134:135], v[124:125], v[62:63]
	v_pk_fma_f32 v[60:61], v[132:133], v[60:61], v[114:115]
	v_pk_mul_f32 v[38:39], v[58:59], v[106:107] op_sel_hi:[0,1]
	v_pk_mul_f32 v[40:41], v[58:59], v[64:65] op_sel_hi:[0,1]
	v_pk_fma_f32 v[64:65], v[130:131], v[40:41], v[112:113]
	v_pk_fma_f32 v[72:73], v[128:129], v[38:39], v[110:111]
	v_mul_f32_e32 v35, v65, v65
	v_mul_f32_e32 v34, v73, v73
	v_fmac_f32_e32 v34, v72, v72
	v_fmac_f32_e32 v35, v64, v64
	v_add_f32_e32 v106, v34, v35
	v_mov_b32_e32 v110, v90
	v_mov_b32_e32 v111, v92
	v_mov_b32_e32 v92, v91
	v_pk_mul_f32 v[110:111], v[58:59], v[110:111] op_sel_hi:[0,1]
	v_pk_mul_f32 v[90:91], v[58:59], v[92:93] op_sel_hi:[0,1]
	v_mul_f32_e32 v108, v61, v61
	v_mul_f32_e32 v114, v63, v63
	v_fmac_f32_e32 v114, v62, v62
	v_fmac_f32_e32 v108, v60, v60
	v_pk_fma_f32 v[90:91], v[142:143], v[90:91], v[104:105]
	v_pk_fma_f32 v[92:93], v[140:141], v[110:111], v[102:103]
	v_mul_f32_e32 v39, v91, v91
	v_mul_f32_e32 v38, v93, v93
	v_fmac_f32_e32 v38, v92, v92
	v_fmac_f32_e32 v39, v90, v90
	v_add_f32_e32 v102, v38, v39
	v_pk_mul_f32 v[38:39], v[58:59], v[94:95] op_sel_hi:[0,1]
	v_pk_mul_f32 v[40:41], v[58:59], v[96:97] op_sel_hi:[0,1]
	v_pk_fma_f32 v[94:95], v[138:139], v[40:41], v[100:101]
	v_pk_fma_f32 v[96:97], v[136:137], v[38:39], v[98:99]
	v_mul_f32_e32 v35, v95, v95
	v_mul_f32_e32 v34, v97, v97
	v_fmac_f32_e32 v34, v96, v96
	v_fmac_f32_e32 v35, v94, v94
	v_add_f32_e32 v98, v34, v35
	v_pk_mul_f32 v[100:101], v[58:59], v[82:83] op_sel_hi:[0,1]
	v_pk_mul_f32 v[82:83], v[58:59], v[84:85] op_sel_hi:[0,1]
	v_pk_fma_f32 v[82:83], v[150:151], v[82:83], v[88:89]
	v_pk_fma_f32 v[84:85], v[148:149], v[100:101], v[86:87]
	v_mul_f32_e32 v39, v83, v83
	v_mul_f32_e32 v38, v85, v85
	v_fmac_f32_e32 v38, v84, v84
	v_fmac_f32_e32 v39, v82, v82
	v_add_f32_e32 v86, v38, v39
	v_mov_b32_e32 v38, v74
	v_mov_b32_e32 v39, v76
	v_mov_b32_e32 v76, v75
	v_pk_mul_f32 v[38:39], v[58:59], v[38:39] op_sel_hi:[0,1]
	v_pk_mul_f32 v[40:41], v[58:59], v[76:77] op_sel_hi:[0,1]
	v_pk_fma_f32 v[74:75], v[146:147], v[40:41], v[80:81]
	v_pk_fma_f32 v[76:77], v[144:145], v[38:39], v[78:79]
	v_mul_f32_e32 v35, v75, v75
	v_mul_f32_e32 v34, v77, v77
	v_fmac_f32_e32 v34, v76, v76
	v_fmac_f32_e32 v35, v74, v74
	v_add_f32_e32 v78, v34, v35
	v_pk_fma_f32 v[44:45], v[154:155], v[44:45], v[48:49]
	s_waitcnt vmcnt(0)
	v_pk_fma_f32 v[40:41], v[158:159], v[54:55], v[56:57]
	v_pk_fma_f32 v[38:39], v[156:157], v[50:51], v[52:53]
	v_mul_f32_e32 v50, v41, v41
	v_mul_f32_e32 v47, v39, v39
	v_fmac_f32_e32 v47, v38, v38
	v_fmac_f32_e32 v50, v40, v40
	v_add_f32_e32 v50, v47, v50
	v_mov_b32_e32 v47, v59
	v_pk_mul_f32 v[46:47], v[58:59], v[46:47] op_sel_hi:[0,1]
	v_pk_fma_f32 v[42:43], v[152:153], v[46:47], v[42:43]
	v_mul_f32_e32 v35, v45, v45
	v_mul_f32_e32 v34, v43, v43
	v_lshl_add_u64 v[46:47], s[36:37], 0, v[0:1]
	v_fmac_f32_e32 v34, v42, v42
	v_fmac_f32_e32 v35, v44, v44
	v_add_co_u32_e32 v46, vcc, s20, v46
	v_add_f32_e32 v48, v34, v35
	v_cvt_pk_bf16_f32 v34, v60, v61
	v_cvt_pk_bf16_f32 v35, v62, v63
	v_cvt_pk_bf16_f32 v36, v72, v73
	v_cvt_pk_bf16_f32 v37, v64, v65
	v_addc_co_u32_e32 v47, vcc, 0, v47, vcc
	global_store_dwordx4 v[46:47], v[34:37], off
	s_nop 1
	v_cvt_pk_bf16_f32 v34, v92, v93
	v_cvt_pk_bf16_f32 v35, v90, v91
	v_cvt_pk_bf16_f32 v36, v96, v97
	v_cvt_pk_bf16_f32 v37, v94, v95
	global_store_dwordx4 v[46:47], v[34:37], off offset:1024
	s_nop 1
	v_cvt_pk_bf16_f32 v34, v84, v85
	v_cvt_pk_bf16_f32 v35, v82, v83
	v_cvt_pk_bf16_f32 v36, v76, v77
	v_cvt_pk_bf16_f32 v37, v74, v75
	global_store_dwordx4 v[46:47], v[34:37], off offset:2048
	s_nop 1
	v_cvt_pk_bf16_f32 v34, v38, v39
	v_cvt_pk_bf16_f32 v35, v40, v41
	v_cvt_pk_bf16_f32 v36, v42, v43
	v_cvt_pk_bf16_f32 v37, v44, v45
	global_store_dwordx4 v[46:47], v[34:37], off offset:3072
	s_nop 1
	v_add_f32_e32 v34, v108, v114
	v_add_f32_e32 v34, v34, v106
	v_add_f32_e32 v34, v102, v34
	v_add_f32_e32 v34, v98, v34
	v_add_f32_e32 v34, v86, v34
	v_add_f32_e32 v34, v78, v34
	v_add_f32_e32 v34, v50, v34
	v_add_f32_e32 v34, v48, v34
	ds_bpermute_b32 v35, v116, v34
	s_waitcnt lgkmcnt(0)
	v_add_f32_e32 v34, v34, v35
	ds_bpermute_b32 v35, v117, v34
	s_waitcnt lgkmcnt(0)
	v_add_f32_e32 v34, v34, v35
	ds_bpermute_b32 v35, v118, v34
	s_waitcnt lgkmcnt(0)
	v_add_f32_e32 v34, v34, v35
	ds_bpermute_b32 v35, v119, v34
	s_waitcnt lgkmcnt(0)
	v_add_f32_e32 v34, v34, v35
	ds_bpermute_b32 v35, v120, v34
	s_waitcnt lgkmcnt(0)
	v_add_f32_e32 v34, v34, v35
	ds_bpermute_b32 v35, v121, v34
	s_and_saveexec_b64 s[34:35], s[40:41]
	s_cbranch_execz .LBB0_635
	s_waitcnt lgkmcnt(0)
	v_add_f32_e32 v34, v34, v35
	v_fmamk_f32 v34, v34, 0x3a000000, v236
	v_mul_f32_e32 v35, 0x4f800000, v34
	v_cmp_gt_f32_e32 vcc, s68, v34
	s_nop 1
	v_cndmask_b32_e32 v34, v34, v35, vcc
	v_sqrt_f32_e32 v35, v34
	s_nop 0
	v_add_u32_e32 v36, -1, v35
	v_fma_f32 v38, -v36, v35, v34
	v_add_u32_e32 v37, 1, v35
	v_cmp_ge_f32_e64 s[42:43], 0, v38
	s_nop 1
	v_cndmask_b32_e64 v36, v35, v36, s[42:43]
	v_fma_f32 v35, -v37, v35, v34
	v_cmp_lt_f32_e64 s[42:43], 0, v35
	s_nop 1
	v_cndmask_b32_e64 v35, v36, v37, s[42:43]
	v_mul_f32_e32 v36, 0x37800000, v35
	v_cndmask_b32_e32 v35, v35, v36, vcc
	v_cmp_class_f32_e32 vcc, v34, v234
	s_nop 1
	v_cndmask_b32_e32 v34, v35, v34, vcc
	v_div_scale_f32 v35, s[22:23], v34, v34, 1.0
	v_rcp_f32_e32 v36, v35
	s_nop 0
	v_fma_f32 v37, -v35, v36, 1.0
	v_fmac_f32_e32 v36, v37, v36
	v_div_scale_f32 v37, vcc, 1.0, v34, 1.0
	v_mul_f32_e32 v38, v37, v36
	v_fma_f32 v39, -v35, v38, v37
	v_fmac_f32_e32 v38, v39, v36
	v_fma_f32 v35, -v35, v38, v37
	v_div_fmas_f32 v35, v35, v36, v38
	v_div_fixup_f32 v34, v35, v34, 1.0
	global_store_dword v1, v34, s[44:45]
	s_branch .LBB0_635

; __device__ __forceinline__ const float* karg(int k) { int kk = k; asm volatile("" : "+s"(kk)); return ((const float* const __attribute__((address_space(4)))*)__builtin_amdgcn_kernarg_segment_ptr())[kk]; }
; #define PIN_TID() int tid = threadIdx.x; asm volatile("" : "+v"(tid)); const int lane = tid & 63, wid = __builtin_amdgcn_readfirstlane(tid >> 6), gw = blockIdx.x * NWAVES + wid; (void)lane; (void)gw
; template <bool FINAL, bool DUMMY = false> __device__ __forceinline__ void norm_rows(const bfu* F, bfu* XB, const float* g1, float* RS, float* xout, int gw, int NGW, int lane, bfu* dummy = nullptr) {
;     int m = gw; if (m >= M) return;
;     v4u fw[4], xw[4];
; #pragma unroll
;     for (int j = 0; j < 4; ++j) { fw[j] = __builtin_nontemporal_load((const v4u*)(F + (size_t)m * DM) + lane + 64 * j); xw[j] = ((const v4u*)(XB + (size_t)m * DM) + lane)[64 * j]; }
; __global__ void __launch_bounds__(NTHR, 2) fwd(Args args) {
;     ...
;         if (XEN(9) && IN_PH()) for (int rep = 0; rep < XREP(9); ++rep) { PIN_TID(); if (XREP(9) > 1 && rep == 0) norm_rows<false, true>(F32, XN, karg(19) + l * DM, RS, nullptr, gw, NGW, lane, PROJ); else if (l + 1 < DEPTH) norm_rows<false>(F32, XN, karg(19) + l * DM, RS, nullptr, gw, NGW, lane); else norm_rows<true>(F32, XN, karg(19) + l * DM, nullptr, out, gw, NGW, lane); }
.LBB0_844:
	s_cmp_le_i32 s58, s20
	s_cselect_b64 s[4:5], -1, 0
	s_and_b64 s[22:23], s[4:5], s[26:27]
	s_andn2_b64 vcc, exec, s[22:23]
	s_cbranch_vccnz .LBB0_860
	v_mov_b32_e32 v0, v232
	s_mov_b64 s[34:35], -1
	v_readfirstlane_b32 s20, v0
	s_ashr_i32 s48, s20, 6
	v_readlane_b32 s20, v255, 25
	s_add_i32 s26, s48, s20
	v_readlane_b32 s20, v255, 30
	s_cmp_eq_u32 s20, 3
	v_and_b32_e32 v116, 63, v0
	s_cbranch_scc1 .LBB0_854
	s_mov_b32 s34, 21
	s_mov_b32 s40, 21
	s_mov_b32 s38, 19
	s_mov_b32 s36, 21
	s_cmpk_gt_i32 s26, 0x3fff
	s_cbranch_scc1 .LBB0_853
	s_ashr_i32 s35, s34, 31
	s_lshl_b64 s[22:23], s[34:35], 3
	s_add_u32 s22, s0, s22
	s_addc_u32 s23, s1, s23
	s_ashr_i32 s41, s40, 31
	s_load_dwordx2 s[34:35], s[22:23], 0x0
	s_lshl_b64 s[22:23], s[40:41], 3
	s_add_u32 s22, s0, s22
	s_addc_u32 s23, s1, s23
	s_ashr_i32 s39, s38, 31
	s_load_dwordx2 s[40:41], s[22:23], 0x0
	s_lshl_b64 s[22:23], s[38:39], 3
	s_add_u32 s22, s0, s22
	s_addc_u32 s23, s1, s23
	s_load_dwordx2 s[22:23], s[22:23], 0x0
	s_ashr_i32 s37, s36, 31
	s_lshl_b64 s[36:37], s[36:37], 3
	s_add_u32 s36, s0, s36
	v_readlane_b32 s20, v255, 30
	s_addc_u32 s37, s1, s37
	s_lshl_b32 s20, s20, 11
	s_load_dwordx2 s[42:43], s[36:37], 0x0
	s_lshl_b64 s[36:37], s[20:21], 2
	s_waitcnt lgkmcnt(0)
	s_add_u32 s44, s22, s36
	s_addc_u32 s45, s23, s37
	s_ashr_i32 s27, s26, 31
	s_lshl_b64 s[22:23], s[26:27], 12
	s_add_u32 s36, s40, s22
	s_addc_u32 s37, s41, s23
	v_lshlrev_b32_e32 v0, 4, v116
	s_add_u32 s22, s34, s22
	v_lshl_add_u64 v[2:3], s[36:37], 0, v[0:1]
	s_mov_b64 s[38:39], 0x18e00000
	s_addc_u32 s23, s35, s23
	s_mov_b32 s20, 0x18e00000
	v_lshl_add_u64 v[4:5], v[2:3], 0, s[38:39]
	v_lshl_add_u64 v[6:7], s[22:23], 0, v[0:1]
	s_mov_b64 s[22:23], 0x2d600000
	v_add_co_u32_e32 v2, vcc, s20, v2
	v_lshl_add_u64 v[8:9], v[6:7], 0, s[22:23]
	s_nop 0
	v_addc_co_u32_e32 v3, vcc, 0, v3, vcc
	s_mov_b32 s20, 0x2d600000
	global_load_dwordx4 v[34:37], v[4:5], off offset:3072
	global_load_dwordx4 v[38:41], v[8:9], off offset:3072 nt
	global_load_dwordx4 v[42:45], v[4:5], off offset:2048
	global_load_dwordx4 v[46:49], v[8:9], off offset:2048 nt
	global_load_dwordx4 v[50:53], v[4:5], off offset:1024
	global_load_dwordx4 v[54:57], v[8:9], off offset:1024 nt
	global_load_dwordx4 v[58:61], v[2:3], off
	v_add_co_u32_e32 v2, vcc, s20, v6
	s_mov_b64 s[22:23], 0x1000
	s_nop 0
	v_addc_co_u32_e32 v3, vcc, 0, v7, vcc
	global_load_dwordx4 v[62:65], v[2:3], off nt
	v_and_b32_e32 v2, 64, v240
	v_add_u32_e32 v2, 64, v2
	v_xor_b32_e32 v3, 1, v240
	v_cmp_lt_i32_e32 vcc, v3, v2
	v_cmp_eq_u32_e64 s[38:39], 0, v116
	s_waitcnt vmcnt(0)
	v_mov_b64_e32 v[30:31], v[38:39]
	v_cndmask_b32_e32 v3, v240, v3, vcc
	v_lshlrev_b32_e32 v117, 2, v3
	v_xor_b32_e32 v3, 2, v240
	v_cmp_lt_i32_e32 vcc, v3, v2
	v_mov_b64_e32 v[10:11], v[50:51]
	v_mov_b64_e32 v[18:19], v[42:43]
	v_cndmask_b32_e32 v3, v240, v3, vcc
	v_lshlrev_b32_e32 v118, 2, v3
	v_xor_b32_e32 v3, 4, v240
	v_cmp_lt_i32_e32 vcc, v3, v2
	v_mov_b64_e32 v[22:23], v[34:35]
	v_mov_b64_e32 v[6:7], v[62:63]
	v_cndmask_b32_e32 v3, v240, v3, vcc
	v_lshlrev_b32_e32 v119, 2, v3
	v_xor_b32_e32 v3, 8, v240
	v_cmp_lt_i32_e32 vcc, v3, v2
	v_mov_b64_e32 v[14:15], v[54:55]
	v_mov_b64_e32 v[26:27], v[46:47]
	v_cndmask_b32_e32 v3, v240, v3, vcc
	v_lshlrev_b32_e32 v120, 2, v3
	v_xor_b32_e32 v3, 16, v240
	v_cmp_lt_i32_e32 vcc, v3, v2
	v_mov_b64_e32 v[12:13], v[52:53]
	v_mov_b64_e32 v[20:21], v[44:45]
	v_cndmask_b32_e32 v3, v240, v3, vcc
	v_lshlrev_b32_e32 v121, 2, v3
	v_xor_b32_e32 v3, 32, v240
	v_cmp_lt_i32_e32 vcc, v3, v2
	v_mov_b64_e32 v[24:25], v[36:37]
	v_mov_b64_e32 v[8:9], v[64:65]
	v_cndmask_b32_e32 v2, v240, v3, vcc
	v_lshlrev_b32_e32 v122, 2, v2
	v_lshlrev_b32_e32 v2, 5, v116
	v_mov_b32_e32 v3, v1
	v_lshl_add_u64 v[66:67], s[44:45], 0, v[2:3]
	v_lshl_add_u64 v[68:69], v[66:67], 0, s[22:23]
	s_mov_b64 s[22:23], 0x1800
	v_lshl_add_u64 v[70:71], v[66:67], 0, s[22:23]
	global_load_dwordx4 v[128:131], v[66:67], off offset:16
	global_load_dwordx4 v[132:135], v[66:67], off
	global_load_dwordx4 v[136:139], v[66:67], off offset:2064
	global_load_dwordx4 v[140:143], v[66:67], off offset:2048
	global_load_dwordx4 v[144:147], v[68:69], off offset:16
	global_load_dwordx4 v[148:151], v[68:69], off
	global_load_dwordx4 v[152:155], v[70:71], off offset:16
	global_load_dwordx4 v[156:159], v[70:71], off
	s_waitcnt vmcnt(0)
	s_lshl_b64 s[22:23], s[26:27], 2
	s_add_u32 s20, s42, s22
	s_addc_u32 s22, s43, s23
	s_add_u32 s42, s20, 0x1c0000
	v_readlane_b32 s20, v255, 26
	s_addc_u32 s43, s22, 0
	s_add_i32 s22, s20, s48
	s_ashr_i32 s23, s22, 31
	s_lshl_b64 s[22:23], s[22:23], 12
	s_add_u32 s44, s34, s22
	s_addc_u32 s45, s35, s23
	s_add_u32 s46, s40, s22
	v_mov_b64_e32 v[2:3], v[58:59]
	s_addc_u32 s47, s41, s23
	s_mov_b32 s20, s26
	v_mov_b64_e32 v[4:5], v[60:61]
	v_mov_b64_e32 v[16:17], v[56:57]
	v_mov_b64_e32 v[28:29], v[48:49]
	v_mov_b64_e32 v[32:33], v[40:41]
	s_branch .LBB0_849

; template <bool FINAL, bool DUMMY = false> __device__ __forceinline__ void norm_rows(const bfu* F, bfu* XB, const float* g1, float* RS, float* xout, int gw, int NGW, int lane, bfu* dummy = nullptr) {
;     ...
;         for (int j = 0; j < 4; ++j) {
;             f[2 * j] = (f32x4){bflo(fw[j].x), bfhi(fw[j].x), bflo(fw[j].y), bfhi(fw[j].y)}; f[2 * j + 1] = (f32x4){bflo(fw[j].z), bfhi(fw[j].z), bflo(fw[j].w), bfhi(fw[j].w)};
;             x[2 * j] = (f32x4){bflo(xw[j].x), bfhi(xw[j].x), bflo(xw[j].y), bfhi(xw[j].y)}; x[2 * j + 1] = (f32x4){bflo(xw[j].z), bfhi(xw[j].z), bflo(xw[j].w), bfhi(xw[j].w)}; }
;         const int mn = m + NGW;
;         if (mn < M) {
; #pragma unroll
;             for (int j = 0; j < 4; ++j) { fw[j] = __builtin_nontemporal_load((const v4u*)(F + (size_t)mn * DM) + lane + 64 * j); xw[j] = ((const v4u*)(XB + (size_t)mn * DM) + lane)[64 * j]; }
;         }
; #pragma unroll
;         for (int k = 0; k < 8; ++k) s += (f[k].x * f[k].x + f[k].y * f[k].y) + (f[k].z * f[k].z + f[k].w * f[k].w);
;         const float rstd1 = 1.f / sqrtf(wave_sum(s) * (1.f / DM) + EPS);
.LBB0_851:
	v_lshlrev_b32_e32 v73, 16, v64
	v_and_b32_e32 v107, 0xffff0000, v64
	v_and_b32_e32 v106, 0xffff0000, v62
	v_lshlrev_b32_e32 v109, 16, v65
	v_and_b32_e32 v65, 0xffff0000, v65
	v_and_b32_e32 v64, 0xffff0000, v63
	v_lshlrev_b32_e32 v72, 16, v62
	v_lshlrev_b32_e32 v108, 16, v63
	v_lshlrev_b32_e32 v94, 16, v56
	v_and_b32_e32 v95, 0xffff0000, v56
	v_lshlrev_b32_e32 v96, 16, v57
	v_and_b32_e32 v97, 0xffff0000, v57
	v_lshlrev_b32_e32 v98, 16, v52
	v_and_b32_e32 v99, 0xffff0000, v52
	v_lshlrev_b32_e32 v100, 16, v53
	v_and_b32_e32 v101, 0xffff0000, v53
	v_lshlrev_b32_e32 v75, 16, v49
	v_lshlrev_b32_e32 v74, 16, v48
	v_and_b32_e32 v77, 0xffff0000, v49
	v_and_b32_e32 v76, 0xffff0000, v48
	v_lshlrev_b32_e32 v86, 16, v42
	v_and_b32_e32 v87, 0xffff0000, v42
	v_lshlrev_b32_e32 v88, 16, v43
	v_and_b32_e32 v89, 0xffff0000, v43
	v_lshlrev_b32_e32 v52, 16, v34
	v_and_b32_e32 v53, 0xffff0000, v34
	v_lshlrev_b32_e32 v56, 16, v35
	v_and_b32_e32 v57, 0xffff0000, v35
	v_lshlrev_b32_e32 v42, 16, v36
	v_and_b32_e32 v43, 0xffff0000, v36
	v_lshlrev_b32_e32 v48, 16, v37
	v_and_b32_e32 v49, 0xffff0000, v37
	v_pk_mul_f32 v[34:35], v[106:107], v[106:107]
	v_pk_mul_f32 v[36:37], v[64:65], v[64:65]
	v_pk_fma_f32 v[34:35], v[72:73], v[72:73], v[34:35]
	v_pk_fma_f32 v[36:37], v[108:109], v[108:109], v[36:37]
	v_and_b32_e32 v93, 0xffff0000, v55
	v_and_b32_e32 v92, 0xffff0000, v54
	v_pk_add_f32 v[34:35], v[34:35], v[36:37]
	v_lshlrev_b32_e32 v91, 16, v55
	v_lshlrev_b32_e32 v90, 16, v54
	v_lshlrev_b32_e32 v82, 16, v46
	v_pk_add_f32 v[34:35], v[34:35], v[34:35] op_sel_hi:[0,1]
	v_pk_mul_f32 v[36:37], v[92:93], v[92:93]
	v_lshlrev_b32_e32 v102, 16, v50
	v_and_b32_e32 v103, 0xffff0000, v50
	v_lshlrev_b32_e32 v104, 16, v51
	v_and_b32_e32 v105, 0xffff0000, v51
	v_lshlrev_b32_e32 v50, 16, v38
	v_and_b32_e32 v51, 0xffff0000, v38
	v_lshlrev_b32_e32 v54, 16, v39
	v_and_b32_e32 v55, 0xffff0000, v39
	v_pk_fma_f32 v[36:37], v[90:91], v[90:91], v[36:37]
	v_mul_f32_e32 v83, v94, v94
	v_mul_f32_e32 v39, v95, v95
	v_mul_f32_e32 v34, v96, v96
	v_mov_b32_e32 v38, v82
	v_lshlrev_b32_e32 v62, 16, v59
	v_and_b32_e32 v63, 0xffff0000, v59
	v_and_b32_e32 v123, 0xffff0000, v46
	v_lshlrev_b32_e32 v84, 16, v47
	v_and_b32_e32 v85, 0xffff0000, v47
	v_lshlrev_b32_e32 v78, 16, v44
	v_and_b32_e32 v79, 0xffff0000, v44
	v_lshlrev_b32_e32 v80, 16, v45
	v_and_b32_e32 v81, 0xffff0000, v45
	v_lshlrev_b32_e32 v46, 16, v40
	v_and_b32_e32 v59, 0xffff0000, v40
	v_lshlrev_b32_e32 v44, 16, v41
	v_and_b32_e32 v45, 0xffff0000, v41
	v_pk_add_f32 v[36:37], v[36:37], v[36:37] op_sel_hi:[0,1]
	v_pk_fma_f32 v[40:41], v[96:97], v[96:97], v[34:35] op_sel_hi:[1,1,0]
	v_pk_add_f32 v[38:39], v[82:83], v[38:39]
	v_lshlrev_b32_e32 v110, 16, v60
	v_and_b32_e32 v111, 0xffff0000, v60
	v_lshlrev_b32_e32 v112, 16, v61
	v_and_b32_e32 v113, 0xffff0000, v61
	v_mul_f32_e32 v40, v123, v123
	v_mul_f32_e32 v34, v84, v84
	v_mul_f32_e32 v36, v85, v85
	v_mul_f32_e32 v60, v82, v82
	v_mov_b32_e32 v61, v39
	v_pk_add_f32 v[38:39], v[60:61], v[40:41]
	v_pk_add_f32 v[34:35], v[34:35], v[36:37]
	v_pk_mul_f32 v[36:37], v[76:77], v[76:77]
	v_pk_add_f32 v[34:35], v[38:39], v[34:35]
	v_pk_fma_f32 v[36:37], v[74:75], v[74:75], v[36:37]
	v_pk_add_f32 v[34:35], v[34:35], v[34:35] op_sel_hi:[0,1]
	v_mul_f32_e32 v47, v50, v50
	v_mul_f32_e32 v39, v51, v51
	v_mul_f32_e32 v34, v54, v54
	v_mov_b32_e32 v38, v46
	v_pk_add_f32 v[36:37], v[36:37], v[36:37] op_sel_hi:[0,1]
	v_pk_fma_f32 v[40:41], v[54:55], v[54:55], v[34:35] op_sel_hi:[1,1,0]
	v_pk_add_f32 v[38:39], v[46:47], v[38:39]
	v_mul_f32_e32 v40, v59, v59
	v_mul_f32_e32 v36, v44, v44
	v_mul_f32_e32 v34, v45, v45
	v_mul_f32_e32 v60, v46, v46
	v_mov_b32_e32 v61, v39
	v_pk_add_f32 v[38:39], v[60:61], v[40:41]
	v_pk_add_f32 v[34:35], v[36:37], v[34:35]
	v_lshlrev_b32_e32 v114, 16, v58
	v_pk_add_f32 v[34:35], v[38:39], v[34:35]
	v_and_b32_e32 v115, 0xffff0000, v58
	v_add_f32_e32 v34, v34, v35
	ds_bpermute_b32 v35, v117, v34
	v_mov_b32_e32 v60, v72
	v_mov_b32_e32 v61, v106
	v_mov_b32_e32 v124, v108
	v_mov_b32_e32 v125, v64
	s_waitcnt lgkmcnt(0)
	v_add_f32_e32 v34, v34, v35
	ds_bpermute_b32 v35, v118, v34
	v_mov_b32_e32 v106, v73
	v_mov_b32_e32 v64, v109
	v_mov_b32_e32 v83, v123
	s_waitcnt lgkmcnt(0)
	v_add_f32_e32 v34, v34, v35
	ds_bpermute_b32 v35, v119, v34
	s_waitcnt lgkmcnt(0)
	v_add_f32_e32 v34, v34, v35
	ds_bpermute_b32 v35, v120, v34
	s_waitcnt lgkmcnt(0)
	v_add_f32_e32 v34, v34, v35
	ds_bpermute_b32 v35, v121, v34
	s_waitcnt lgkmcnt(0)
	v_add_f32_e32 v34, v34, v35
	ds_bpermute_b32 v35, v122, v34
	s_waitcnt lgkmcnt(0)
; __device__ __forceinline__ unsigned pk2(float lo, float hi) { return pg8::cvt_pk_bf16(lo, hi); }
; template <bool FINAL, bool DUMMY = false> __device__ __forceinline__ void norm_rows(const bfu* F, bfu* XB, const float* g1, float* RS, float* xout, int gw, int NGW, int lane, bfu* dummy = nullptr) {
;     ...
;         const float rstd1 = 1.f / sqrtf(wave_sum(s) * (1.f / DM) + EPS);
;         float s2 = 0.f;
; #pragma unroll
;         for (int k = 0; k < 8; ++k) { const f32x4 gg = ((const f32x4*)g1)[2 * lane + 128 * (k >> 1) + (k & 1)]; x[k] = x[k] + f[k] * rstd1 * gg; s2 += (x[k].x * x[k].x + x[k].y * x[k].y) + (x[k].z * x[k].z + x[k].w * x[k].w); }
;         if (FINAL) { f32x4* xo = (f32x4*)(xout + (size_t)m * DM);
; #pragma unroll
;             for (int k = 0; k < 8; ++k) __builtin_nontemporal_store(x[k], xo + 2 * lane + 128 * (k >> 1) + (k & 1));
;         } else {
;             v4u* xr = (v4u*)((DUMMY ? dummy : XB) + (size_t)m * DM) + lane;
; #pragma unroll
;             for (int j = 0; j < 4; ++j) { v4u w; w.x = pk2(x[2 * j].x, x[2 * j].y); w.y = pk2(x[2 * j].z, x[2 * j].w); w.z = pk2(x[2 * j + 1].x, x[2 * j + 1].y); w.w = pk2(x[2 * j + 1].z, x[2 * j + 1].w); xr[64 * j] = w; }
;             const float rstd2 = 1.f / sqrtf(wave_sum(s2) * (1.f / DM) + EPS);
;             if (lane == 0) (DUMMY ? (float*)dummy + (size_t)M * DM : RS)[m] = rstd2;
	v_add_f32_e32 v34, v34, v35
	v_fmamk_f32 v34, v34, 0x3a000000, v236
	v_cmp_gt_f32_e32 vcc, s68, v34
	v_mul_f32_e32 v35, 0x4f800000, v34
	s_nop 0
	v_cndmask_b32_e32 v34, v34, v35, vcc
	v_sqrt_f32_e32 v35, v34
	s_nop 0
	v_add_u32_e32 v36, -1, v35
	v_fma_f32 v37, -v36, v35, v34
	v_cmp_ge_f32_e64 s[40:41], 0, v37
	v_add_u32_e32 v37, 1, v35
	s_nop 0
	v_cndmask_b32_e64 v36, v35, v36, s[40:41]
	v_fma_f32 v35, -v37, v35, v34
	v_cmp_lt_f32_e64 s[40:41], 0, v35
	s_nop 1
	v_cndmask_b32_e64 v35, v36, v37, s[40:41]
	v_mul_f32_e32 v36, 0x37800000, v35
	v_cndmask_b32_e32 v35, v35, v36, vcc
	v_cmp_class_f32_e32 vcc, v34, v234
	s_nop 1
	v_cndmask_b32_e32 v34, v35, v34, vcc
	v_div_scale_f32 v35, s[22:23], v34, v34, 1.0
	v_rcp_f32_e32 v36, v35
	s_mov_b32 s22, 0x18e00000
	v_fma_f32 v37, -v35, v36, 1.0
	v_fmac_f32_e32 v36, v37, v36
	v_div_scale_f32 v37, vcc, 1.0, v34, 1.0
	v_mul_f32_e32 v38, v37, v36
	v_fma_f32 v39, -v35, v38, v37
	v_fmac_f32_e32 v38, v39, v36
	v_fma_f32 v35, -v35, v38, v37
	v_div_fmas_f32 v35, v35, v36, v38
	v_div_fixup_f32 v58, v35, v34, 1.0
	v_pk_mul_f32 v[60:61], v[58:59], v[60:61] op_sel_hi:[0,1]
	v_pk_mul_f32 v[124:125], v[58:59], v[124:125] op_sel_hi:[0,1]
	v_pk_mul_f32 v[50:51], v[58:59], v[50:51] op_sel_hi:[0,1]
	v_pk_mul_f32 v[54:55], v[58:59], v[54:55] op_sel_hi:[0,1]
	v_pk_mul_f32 v[44:45], v[58:59], v[44:45] op_sel_hi:[0,1]
	v_pk_fma_f32 v[62:63], v[134:135], v[124:125], v[62:63]
	v_pk_fma_f32 v[60:61], v[132:133], v[60:61], v[114:115]
	v_pk_mul_f32 v[38:39], v[58:59], v[106:107] op_sel_hi:[0,1]
	v_pk_mul_f32 v[40:41], v[58:59], v[64:65] op_sel_hi:[0,1]
	v_pk_fma_f32 v[64:65], v[130:131], v[40:41], v[112:113]
	v_pk_fma_f32 v[72:73], v[128:129], v[38:39], v[110:111]
	v_mul_f32_e32 v35, v65, v65
	v_mul_f32_e32 v34, v73, v73
	v_fmac_f32_e32 v34, v72, v72
	v_fmac_f32_e32 v35, v64, v64
	v_add_f32_e32 v106, v34, v35
	v_mov_b32_e32 v110, v90
	v_mov_b32_e32 v111, v92
	v_mov_b32_e32 v92, v91
	v_pk_mul_f32 v[110:111], v[58:59], v[110:111] op_sel_hi:[0,1]
	v_pk_mul_f32 v[90:91], v[58:59], v[92:93] op_sel_hi:[0,1]
	v_mul_f32_e32 v108, v61, v61
	v_mul_f32_e32 v114, v63, v63
	v_fmac_f32_e32 v114, v62, v62
	v_fmac_f32_e32 v108, v60, v60
	v_pk_fma_f32 v[90:91], v[142:143], v[90:91], v[104:105]
	v_pk_fma_f32 v[92:93], v[140:141], v[110:111], v[102:103]
	v_mul_f32_e32 v39, v91, v91
	v_mul_f32_e32 v38, v93, v93
	v_fmac_f32_e32 v38, v92, v92
	v_fmac_f32_e32 v39, v90, v90
	v_add_f32_e32 v102, v38, v39
	v_pk_mul_f32 v[38:39], v[58:59], v[94:95] op_sel_hi:[0,1]
	v_pk_mul_f32 v[40:41], v[58:59], v[96:97] op_sel_hi:[0,1]
	v_pk_fma_f32 v[94:95], v[138:139], v[40:41], v[100:101]
	v_pk_fma_f32 v[96:97], v[136:137], v[38:39], v[98:99]
	v_mul_f32_e32 v35, v95, v95
	v_mul_f32_e32 v34, v97, v97
	v_fmac_f32_e32 v34, v96, v96
	v_fmac_f32_e32 v35, v94, v94
	v_add_f32_e32 v98, v34, v35
	v_pk_mul_f32 v[100:101], v[58:59], v[82:83] op_sel_hi:[0,1]
	v_pk_mul_f32 v[82:83], v[58:59], v[84:85] op_sel_hi:[0,1]
	v_pk_fma_f32 v[82:83], v[150:151], v[82:83], v[88:89]
	v_pk_fma_f32 v[84:85], v[148:149], v[100:101], v[86:87]
	v_mul_f32_e32 v39, v83, v83
	v_mul_f32_e32 v38, v85, v85
	v_fmac_f32_e32 v38, v84, v84
	v_fmac_f32_e32 v39, v82, v82
	v_add_f32_e32 v86, v38, v39
	v_mov_b32_e32 v38, v74
	v_mov_b32_e32 v39, v76
	v_mov_b32_e32 v76, v75
	v_pk_mul_f32 v[38:39], v[58:59], v[38:39] op_sel_hi:[0,1]
	v_pk_mul_f32 v[40:41], v[58:59], v[76:77] op_sel_hi:[0,1]
	v_pk_fma_f32 v[74:75], v[146:147], v[40:41], v[80:81]
	v_pk_fma_f32 v[76:77], v[144:145], v[38:39], v[78:79]
	v_mul_f32_e32 v35, v75, v75
	v_mul_f32_e32 v34, v77, v77
	v_fmac_f32_e32 v34, v76, v76
	v_fmac_f32_e32 v35, v74, v74
	v_add_f32_e32 v78, v34, v35
	v_pk_fma_f32 v[44:45], v[154:155], v[44:45], v[48:49]
	s_waitcnt vmcnt(0)
	v_pk_fma_f32 v[40:41], v[158:159], v[54:55], v[56:57]
	v_pk_fma_f32 v[38:39], v[156:157], v[50:51], v[52:53]
	v_mul_f32_e32 v50, v41, v41
	v_mul_f32_e32 v47, v39, v39
	v_fmac_f32_e32 v47, v38, v38
	v_fmac_f32_e32 v50, v40, v40
	v_add_f32_e32 v50, v47, v50
	v_mov_b32_e32 v47, v59
	v_pk_mul_f32 v[46:47], v[58:59], v[46:47] op_sel_hi:[0,1]
	v_pk_fma_f32 v[42:43], v[152:153], v[46:47], v[42:43]
	v_mul_f32_e32 v35, v45, v45
	v_mul_f32_e32 v34, v43, v43
	v_lshl_add_u64 v[46:47], s[36:37], 0, v[0:1]
	v_fmac_f32_e32 v34, v42, v42
	v_fmac_f32_e32 v35, v44, v44
	v_add_co_u32_e32 v46, vcc, s22, v46
	v_add_f32_e32 v48, v34, v35
	v_cvt_pk_bf16_f32 v34, v60, v61
	v_cvt_pk_bf16_f32 v35, v62, v63
	v_cvt_pk_bf16_f32 v36, v72, v73
	v_cvt_pk_bf16_f32 v37, v64, v65
	v_addc_co_u32_e32 v47, vcc, 0, v47, vcc
	global_store_dwordx4 v[46:47], v[34:37], off
	s_nop 1
	v_cvt_pk_bf16_f32 v34, v92, v93
	v_cvt_pk_bf16_f32 v35, v90, v91
	v_cvt_pk_bf16_f32 v36, v96, v97
	v_cvt_pk_bf16_f32 v37, v94, v95
	global_store_dwordx4 v[46:47], v[34:37], off offset:1024
	s_nop 1
	v_cvt_pk_bf16_f32 v34, v84, v85
	v_cvt_pk_bf16_f32 v35, v82, v83
	v_cvt_pk_bf16_f32 v36, v76, v77
	v_cvt_pk_bf16_f32 v37, v74, v75
	global_store_dwordx4 v[46:47], v[34:37], off offset:2048
	s_nop 1
	v_cvt_pk_bf16_f32 v34, v38, v39
	v_cvt_pk_bf16_f32 v35, v40, v41
	v_cvt_pk_bf16_f32 v36, v42, v43
	v_cvt_pk_bf16_f32 v37, v44, v45
	global_store_dwordx4 v[46:47], v[34:37], off offset:3072
	s_nop 1
	v_add_f32_e32 v34, v108, v114
	v_add_f32_e32 v34, v34, v106
	v_add_f32_e32 v34, v102, v34
	v_add_f32_e32 v34, v98, v34
	v_add_f32_e32 v34, v86, v34
	v_add_f32_e32 v34, v78, v34
	v_add_f32_e32 v34, v50, v34
	v_add_f32_e32 v34, v48, v34
	ds_bpermute_b32 v35, v117, v34
	s_waitcnt lgkmcnt(0)
	v_add_f32_e32 v34, v34, v35
	ds_bpermute_b32 v35, v118, v34
	s_waitcnt lgkmcnt(0)
	v_add_f32_e32 v34, v34, v35
	ds_bpermute_b32 v35, v119, v34
	s_waitcnt lgkmcnt(0)
	v_add_f32_e32 v34, v34, v35
	ds_bpermute_b32 v35, v120, v34
	s_waitcnt lgkmcnt(0)
	v_add_f32_e32 v34, v34, v35
	ds_bpermute_b32 v35, v121, v34
	s_waitcnt lgkmcnt(0)
	v_add_f32_e32 v34, v34, v35
	ds_bpermute_b32 v35, v122, v34
	s_and_saveexec_b64 s[34:35], s[38:39]
	s_cbranch_execz .LBB0_848
	s_waitcnt lgkmcnt(0)
	v_add_f32_e32 v34, v34, v35
	v_fmamk_f32 v34, v34, 0x3a000000, v236
	v_mul_f32_e32 v35, 0x4f800000, v34
	v_cmp_gt_f32_e32 vcc, s68, v34
	s_nop 1
	v_cndmask_b32_e32 v34, v34, v35, vcc
	v_sqrt_f32_e32 v35, v34
	s_nop 0
	v_add_u32_e32 v36, -1, v35
	v_fma_f32 v38, -v36, v35, v34
	v_add_u32_e32 v37, 1, v35
	v_cmp_ge_f32_e64 s[40:41], 0, v38
	s_nop 1
	v_cndmask_b32_e64 v36, v35, v36, s[40:41]
	v_fma_f32 v35, -v37, v35, v34
	v_cmp_lt_f32_e64 s[40:41], 0, v35
	s_nop 1
	v_cndmask_b32_e64 v35, v36, v37, s[40:41]
	v_mul_f32_e32 v36, 0x37800000, v35
	v_cndmask_b32_e32 v35, v35, v36, vcc
	v_cmp_class_f32_e32 vcc, v34, v234
	s_nop 1
	v_cndmask_b32_e32 v34, v35, v34, vcc
	v_div_scale_f32 v35, s[22:23], v34, v34, 1.0
	v_rcp_f32_e32 v36, v35
	s_nop 0
	v_fma_f32 v37, -v35, v36, 1.0
	v_fmac_f32_e32 v36, v37, v36
	v_div_scale_f32 v37, vcc, 1.0, v34, 1.0
	v_mul_f32_e32 v38, v37, v36
	v_fma_f32 v39, -v35, v38, v37
	v_fmac_f32_e32 v38, v39, v36
	v_fma_f32 v35, -v35, v38, v37
	v_div_fmas_f32 v35, v35, v36, v38
	v_div_fixup_f32 v34, v35, v34, 1.0
	global_store_dword v1, v34, s[42:43]
	s_branch .LBB0_848
